# phase-9 K-loop: 2x s_nop 15 ahead of the vmcnt wait of the DMA-heavy load sections (tests whether pacing the loader changes throughput)
# speedup vs baseline: 1.0032x; 1.0032x over previous
; #define PG8_LDA(dst, b, h) do { _Pragma("unroll") for (int m = 0; m < 4; ++m) _Pragma("unroll") for (int k = 0; k < 2; ++k) dst[m][k] = *(const LAS bf16x8*)(lds + PG8_SA(b, h) + aoff + m * 2048 + k * 1024); } while (0)
; #define PG8_LDB(dst, b, h) do { _Pragma("unroll") for (int n = 0; n < 2; ++n) _Pragma("unroll") for (int k = 0; k < 2; ++k) dst[n][k] = *(const LAS bf16x8*)(lds + PG8_SB(b, h) + boff + n * 2048 + k * 1024); } while (0)
; #define PG8_MMA(ai, bj, At, Bt) do { __builtin_amdgcn_s_setprio(1); _Pragma("unroll") for (int m = 0; m < 4; ++m) _Pragma("unroll") for (int n = 0; n < 2; ++n) _Pragma("unroll") for (int k = 0; k < 2; ++k) \
;         acc[ai][bj][m][n] = __builtin_amdgcn_mfma_f32_16x16x32_bf16(Bt[n][k], At[m][k], acc[ai][bj][m][n], 0, 0, 0); __builtin_amdgcn_s_setprio(0); } while (0)
; #define PG8_WAIT_V(n) asm volatile("s_waitcnt vmcnt(" #n ")" ::: "memory")
; #define PG8_WAIT_L(n) asm volatile("s_waitcnt lgkmcnt(" #n ")" ::: "memory")
; #define PG8_BAR __builtin_amdgcn_s_barrier()
; #define PG8_SCHED __builtin_amdgcn_sched_barrier(0)
; template <class Epi, class Addr, bool ALIGN_EPI = true, class Order = StaticOrder>
; __device__ __forceinline__ void gemm_phase(LAS unsigned char* lds, const Gemm g, const Order& S, const Epi& E, const int wid) {
;     ...
;         for (int t = 0; t < nt; t += 2) {
;             const bool last = (t == nt - 2);
;             const char* a1 = cA + (size_t)(t + 1) * kstep;
;             const char* a2 = last ? nA : cA + (size_t)(t + 2) * kstep; const char* b2 = last ? nB : cB + (size_t)(t + 2) * kstep;
;             const char* a3 = a2 + kstep; const char* b3 = b2 + kstep;
;             PG8_LDB(B0, 0, 0); PG8_LDB(B1, 0, 1); PG8_SCHED; PG8_LDA(At, 0, 0); PG8_STAGE(PG8_SA(1, 1), a1 + hstepA, voffA);
;             PG8_WAIT_V(8); PG8_WAIT_L(0); PG8_BAR; PG8_MMA(0, 0, At, B0); PG8_MMA(0, 1, At, B1); PG8_BAR; PG8_SCHED;
;             PG8_LDA(At, 0, 1); PG8_STAGE(PG8_SB(0, 0), b2, voffB); PG8_STAGE(PG8_SB(0, 1), b2 + hstepB, voffB); PG8_STAGE(PG8_SA(0, 0), a2, voffA);
;             PG8_WAIT_V(8); PG8_WAIT_L(0); PG8_BAR; PG8_MMA(1, 0, At, B0); PG8_MMA(1, 1, At, B1); PG8_BAR; PG8_SCHED;
.LBB0_951:
	ds_read_b128 v[120:123], v200
	ds_read_b128 v[132:135], v200 offset:1024
	ds_read_b128 v[136:139], v200 offset:2048
	ds_read_b128 v[140:143], v200 offset:3072
	ds_read_b128 v[144:147], v201
	ds_read_b128 v[148:151], v201 offset:1024
	ds_read_b128 v[152:155], v201 offset:2048
	ds_read_b128 v[156:159], v201 offset:3072
	s_add_u32 s14, s12, 0x100
	s_addc_u32 s15, s13, 0
	s_cmp_eq_u32 s18, 60
	s_cselect_b32 s76, s67, s14
	s_cselect_b32 s77, s11, s15
	s_cselect_b32 s74, s73, vcc_lo
	s_cselect_b32 s75, s65, vcc_hi
	s_add_u32 s16, s76, 0x80
	s_addc_u32 s17, s77, 0
	ds_read_b128 v[160:163], v202
	ds_read_b128 v[164:167], v202 offset:1024
	ds_read_b128 v[168:171], v202 offset:2048
	ds_read_b128 v[172:175], v202 offset:3072
	ds_read_b128 v[186:189], v202 offset:4096
	ds_read_b128 v[208:211], v202 offset:5120
	ds_read_b128 v[212:215], v202 offset:6144
	ds_read_b128 v[216:219], v202 offset:7168
	s_add_u32 s12, s12, 0x100080
	s_addc_u32 s13, s13, 0
	s_mov_b32 s19, m0
	s_mov_b32 m0, s96
	s_nop 0
	global_load_lds_dwordx4 v190, s[12:13]
	s_mov_b32 m0, s97
	s_nop 0
	global_load_lds_dwordx4 v192, s[12:13]
	s_mov_b32 m0, s19
	s_waitcnt vmcnt(8)
	s_waitcnt lgkmcnt(0)
	s_barrier
	s_setprio 1
	s_waitcnt lgkmcnt(7)
	v_mfma_f32_16x16x32_bf16 v[128:131], v[120:123], v[160:163], v[128:131]
	v_mfma_f32_16x16x32_bf16 v[56:59], v[136:139], v[160:163], v[56:59]
	s_waitcnt lgkmcnt(5)
	v_mfma_f32_16x16x32_bf16 v[116:119], v[120:123], v[168:171], v[116:119]
	v_mfma_f32_16x16x32_bf16 v[40:43], v[136:139], v[168:171], v[40:43]
	s_waitcnt lgkmcnt(3)
	v_mfma_f32_16x16x32_bf16 v[108:111], v[120:123], v[186:189], v[108:111]
	v_mfma_f32_16x16x32_bf16 v[52:55], v[136:139], v[186:189], v[52:55]
	s_waitcnt lgkmcnt(1)
	v_mfma_f32_16x16x32_bf16 v[104:107], v[120:123], v[212:215], v[104:107]
	v_mfma_f32_16x16x32_bf16 v[32:35], v[136:139], v[212:215], v[32:35]
	v_mfma_f32_16x16x32_bf16 v[128:131], v[132:135], v[164:167], v[128:131]
	v_mfma_f32_16x16x32_bf16 v[56:59], v[140:143], v[164:167], v[56:59]
	v_mfma_f32_16x16x32_bf16 v[116:119], v[132:135], v[172:175], v[116:119]
	v_mfma_f32_16x16x32_bf16 v[40:43], v[140:143], v[172:175], v[40:43]
	v_mfma_f32_16x16x32_bf16 v[108:111], v[132:135], v[208:211], v[108:111]
	v_mfma_f32_16x16x32_bf16 v[52:55], v[140:143], v[208:211], v[52:55]
	s_waitcnt lgkmcnt(0)
	v_mfma_f32_16x16x32_bf16 v[104:107], v[132:135], v[216:219], v[104:107]
	v_mfma_f32_16x16x32_bf16 v[32:35], v[140:143], v[216:219], v[32:35]
	s_setprio 0
	s_setprio 1
	v_mfma_f32_16x16x32_bf16 v[124:127], v[144:147], v[160:163], v[124:127]
	v_mfma_f32_16x16x32_bf16 v[60:63], v[152:155], v[160:163], v[60:63]
	v_mfma_f32_16x16x32_bf16 v[112:115], v[144:147], v[168:171], v[112:115]
	v_mfma_f32_16x16x32_bf16 v[44:47], v[152:155], v[168:171], v[44:47]
	v_mfma_f32_16x16x32_bf16 v[100:103], v[144:147], v[186:189], v[100:103]
	v_mfma_f32_16x16x32_bf16 v[48:51], v[152:155], v[186:189], v[48:51]
	v_mfma_f32_16x16x32_bf16 v[96:99], v[144:147], v[212:215], v[96:99]
	v_mfma_f32_16x16x32_bf16 v[36:39], v[152:155], v[212:215], v[36:39]
	v_mfma_f32_16x16x32_bf16 v[124:127], v[148:151], v[164:167], v[124:127]
	v_mfma_f32_16x16x32_bf16 v[60:63], v[156:159], v[164:167], v[60:63]
	v_mfma_f32_16x16x32_bf16 v[112:115], v[148:151], v[172:175], v[112:115]
	v_mfma_f32_16x16x32_bf16 v[44:47], v[156:159], v[172:175], v[44:47]
	v_mfma_f32_16x16x32_bf16 v[100:103], v[148:151], v[208:211], v[100:103]
	v_mfma_f32_16x16x32_bf16 v[48:51], v[156:159], v[208:211], v[48:51]
	v_mfma_f32_16x16x32_bf16 v[96:99], v[148:151], v[216:219], v[96:99]
	v_mfma_f32_16x16x32_bf16 v[36:39], v[156:159], v[216:219], v[36:39]
	s_setprio 0
	s_barrier
	ds_read_b128 v[160:163], v202 offset:16384
	ds_read_b128 v[164:167], v202 offset:17408
	ds_read_b128 v[168:171], v202 offset:18432
	ds_read_b128 v[172:175], v202 offset:19456
	ds_read_b128 v[186:189], v202 offset:20480
	ds_read_b128 v[208:211], v202 offset:21504
	ds_read_b128 v[212:215], v202 offset:22528
	ds_read_b128 v[216:219], v202 offset:23552
	s_mov_b32 s12, m0
	s_mov_b32 m0, s80
	s_nop 0
	global_load_lds_dwordx4 v191, s[74:75]
	s_mov_b32 m0, s81
	s_nop 0
	global_load_lds_dwordx4 v193, s[74:75]
	s_mov_b32 m0, s12
	s_add_u32 s12, s74, 0x100000
	s_addc_u32 s13, s75, 0
	s_mov_b32 s19, m0
	s_mov_b32 m0, s82
	s_nop 0
	global_load_lds_dwordx4 v191, s[12:13]
	s_mov_b32 m0, s83
	s_nop 0
	global_load_lds_dwordx4 v193, s[12:13]
	s_mov_b32 m0, s19
	s_mov_b32 s12, m0
	s_mov_b32 m0, s79
	s_nop 0
	global_load_lds_dwordx4 v190, s[76:77]
	s_mov_b32 m0, s84
	s_nop 0
	global_load_lds_dwordx4 v192, s[76:77]
	s_mov_b32 m0, s12
	s_nop 15
	s_nop 15
	s_waitcnt vmcnt(8)
	s_waitcnt lgkmcnt(0)
	s_barrier
; #define PG8_LDA(dst, b, h) do { _Pragma("unroll") for (int m = 0; m < 4; ++m) _Pragma("unroll") for (int k = 0; k < 2; ++k) dst[m][k] = *(const LAS bf16x8*)(lds + PG8_SA(b, h) + aoff + m * 2048 + k * 1024); } while (0)
; #define PG8_LDB(dst, b, h) do { _Pragma("unroll") for (int n = 0; n < 2; ++n) _Pragma("unroll") for (int k = 0; k < 2; ++k) dst[n][k] = *(const LAS bf16x8*)(lds + PG8_SB(b, h) + boff + n * 2048 + k * 1024); } while (0)
; #define PG8_MMA(ai, bj, At, Bt) do { __builtin_amdgcn_s_setprio(1); _Pragma("unroll") for (int m = 0; m < 4; ++m) _Pragma("unroll") for (int n = 0; n < 2; ++n) _Pragma("unroll") for (int k = 0; k < 2; ++k) \
;         acc[ai][bj][m][n] = __builtin_amdgcn_mfma_f32_16x16x32_bf16(Bt[n][k], At[m][k], acc[ai][bj][m][n], 0, 0, 0); __builtin_amdgcn_s_setprio(0); } while (0)
; #define PG8_WAIT_V(n) asm volatile("s_waitcnt vmcnt(" #n ")" ::: "memory")
; #define PG8_WAIT_L(n) asm volatile("s_waitcnt lgkmcnt(" #n ")" ::: "memory")
; #define PG8_BAR __builtin_amdgcn_s_barrier()
; #define PG8_SCHED __builtin_amdgcn_sched_barrier(0)
; template <class Epi, class Addr, bool ALIGN_EPI = true, class Order = StaticOrder>
; __device__ __forceinline__ void gemm_phase(LAS unsigned char* lds, const Gemm g, const Order& S, const Epi& E, const int wid) {
;     ...
;             PG8_WAIT_V(8); PG8_WAIT_L(0); PG8_BAR; PG8_MMA(1, 0, At, B0); PG8_MMA(1, 1, At, B1); PG8_BAR; PG8_SCHED;
;             PG8_LDB(B0, 1, 0); PG8_LDB(B1, 1, 1); PG8_SCHED; PG8_LDA(At, 1, 0); PG8_STAGE(PG8_SA(0, 1), a2 + hstepA, voffA);
;             PG8_WAIT_V(8); PG8_WAIT_L(0); PG8_BAR; PG8_MMA(0, 0, At, B0); PG8_MMA(0, 1, At, B1); PG8_BAR; PG8_SCHED;
	s_setprio 1
	s_waitcnt lgkmcnt(7)
	v_mfma_f32_16x16x32_bf16 v[92:95], v[120:123], v[160:163], v[92:95]
	v_mfma_f32_16x16x32_bf16 v[24:27], v[136:139], v[160:163], v[24:27]
	s_waitcnt lgkmcnt(5)
	v_mfma_f32_16x16x32_bf16 v[84:87], v[120:123], v[168:171], v[84:87]
	v_mfma_f32_16x16x32_bf16 v[20:23], v[136:139], v[168:171], v[20:23]
	s_waitcnt lgkmcnt(3)
	v_mfma_f32_16x16x32_bf16 v[76:79], v[120:123], v[186:189], v[76:79]
	v_mfma_f32_16x16x32_bf16 v[0:3], v[136:139], v[186:189], v[0:3]
	s_waitcnt lgkmcnt(1)
	v_mfma_f32_16x16x32_bf16 v[72:75], v[120:123], v[212:215], v[72:75]
	v_mfma_f32_16x16x32_bf16 v[8:11], v[136:139], v[212:215], v[8:11]
	v_mfma_f32_16x16x32_bf16 v[92:95], v[132:135], v[164:167], v[92:95]
	v_mfma_f32_16x16x32_bf16 v[24:27], v[140:143], v[164:167], v[24:27]
	v_mfma_f32_16x16x32_bf16 v[84:87], v[132:135], v[172:175], v[84:87]
	v_mfma_f32_16x16x32_bf16 v[20:23], v[140:143], v[172:175], v[20:23]
	v_mfma_f32_16x16x32_bf16 v[76:79], v[132:135], v[208:211], v[76:79]
	v_mfma_f32_16x16x32_bf16 v[0:3], v[140:143], v[208:211], v[0:3]
	s_waitcnt lgkmcnt(0)
	v_mfma_f32_16x16x32_bf16 v[72:75], v[132:135], v[216:219], v[72:75]
	v_mfma_f32_16x16x32_bf16 v[8:11], v[140:143], v[216:219], v[8:11]
	s_setprio 0
	s_setprio 1
	v_mfma_f32_16x16x32_bf16 v[88:91], v[144:147], v[160:163], v[88:91]
	v_mfma_f32_16x16x32_bf16 v[28:31], v[152:155], v[160:163], v[28:31]
	v_mfma_f32_16x16x32_bf16 v[80:83], v[144:147], v[168:171], v[80:83]
	v_mfma_f32_16x16x32_bf16 v[16:19], v[152:155], v[168:171], v[16:19]
	v_mfma_f32_16x16x32_bf16 v[68:71], v[144:147], v[186:189], v[68:71]
	v_mfma_f32_16x16x32_bf16 v[4:7], v[152:155], v[186:189], v[4:7]
	v_mfma_f32_16x16x32_bf16 v[64:67], v[144:147], v[212:215], v[64:67]
	v_mfma_f32_16x16x32_bf16 v[12:15], v[152:155], v[212:215], v[12:15]
	v_mfma_f32_16x16x32_bf16 v[88:91], v[148:151], v[164:167], v[88:91]
	v_mfma_f32_16x16x32_bf16 v[28:31], v[156:159], v[164:167], v[28:31]
	v_mfma_f32_16x16x32_bf16 v[80:83], v[148:151], v[172:175], v[80:83]
	v_mfma_f32_16x16x32_bf16 v[16:19], v[156:159], v[172:175], v[16:19]
	v_mfma_f32_16x16x32_bf16 v[68:71], v[148:151], v[208:211], v[68:71]
	v_mfma_f32_16x16x32_bf16 v[4:7], v[156:159], v[208:211], v[4:7]
	v_mfma_f32_16x16x32_bf16 v[64:67], v[148:151], v[216:219], v[64:67]
	v_mfma_f32_16x16x32_bf16 v[12:15], v[156:159], v[216:219], v[12:15]
	s_setprio 0
	s_barrier
	ds_read_b128 v[120:123], v203
	ds_read_b128 v[132:135], v203 offset:1024
	ds_read_b128 v[136:139], v203 offset:2048
	ds_read_b128 v[140:143], v203 offset:3072
	ds_read_b128 v[144:147], v204
	ds_read_b128 v[148:151], v204 offset:1024
	ds_read_b128 v[152:155], v204 offset:2048
	ds_read_b128 v[156:159], v204 offset:3072
	ds_read_b128 v[160:163], v202 offset:32768
	ds_read_b128 v[164:167], v202 offset:33792
	ds_read_b128 v[168:171], v202 offset:34816
	ds_read_b128 v[172:175], v202 offset:35840
	ds_read_b128 v[186:189], v202 offset:36864
	ds_read_b128 v[208:211], v202 offset:37888
	ds_read_b128 v[212:215], v202 offset:38912
	ds_read_b128 v[216:219], v202 offset:39936
	s_add_u32 s12, s76, 0x100000
	s_addc_u32 s13, s77, 0
	s_mov_b32 s19, m0
	s_mov_b32 m0, s85
	s_nop 0
	global_load_lds_dwordx4 v190, s[12:13]
	s_mov_b32 m0, s86
	s_nop 0
	global_load_lds_dwordx4 v192, s[12:13]
	s_mov_b32 m0, s19
	s_waitcnt vmcnt(8)
	s_waitcnt lgkmcnt(0)
	s_barrier
	s_setprio 1
	s_waitcnt lgkmcnt(7)
	v_mfma_f32_16x16x32_bf16 v[128:131], v[120:123], v[160:163], v[128:131]
	v_mfma_f32_16x16x32_bf16 v[56:59], v[136:139], v[160:163], v[56:59]
	s_waitcnt lgkmcnt(5)
	v_mfma_f32_16x16x32_bf16 v[116:119], v[120:123], v[168:171], v[116:119]
	v_mfma_f32_16x16x32_bf16 v[40:43], v[136:139], v[168:171], v[40:43]
	s_waitcnt lgkmcnt(3)
	v_mfma_f32_16x16x32_bf16 v[108:111], v[120:123], v[186:189], v[108:111]
	v_mfma_f32_16x16x32_bf16 v[52:55], v[136:139], v[186:189], v[52:55]
	s_waitcnt lgkmcnt(1)
	v_mfma_f32_16x16x32_bf16 v[104:107], v[120:123], v[212:215], v[104:107]
	v_mfma_f32_16x16x32_bf16 v[32:35], v[136:139], v[212:215], v[32:35]
	v_mfma_f32_16x16x32_bf16 v[128:131], v[132:135], v[164:167], v[128:131]
	v_mfma_f32_16x16x32_bf16 v[56:59], v[140:143], v[164:167], v[56:59]
	v_mfma_f32_16x16x32_bf16 v[116:119], v[132:135], v[172:175], v[116:119]
	v_mfma_f32_16x16x32_bf16 v[40:43], v[140:143], v[172:175], v[40:43]
	v_mfma_f32_16x16x32_bf16 v[108:111], v[132:135], v[208:211], v[108:111]
	v_mfma_f32_16x16x32_bf16 v[52:55], v[140:143], v[208:211], v[52:55]
	s_waitcnt lgkmcnt(0)
	v_mfma_f32_16x16x32_bf16 v[104:107], v[132:135], v[216:219], v[104:107]
	v_mfma_f32_16x16x32_bf16 v[32:35], v[140:143], v[216:219], v[32:35]
	s_setprio 0
	s_setprio 1
	v_mfma_f32_16x16x32_bf16 v[124:127], v[144:147], v[160:163], v[124:127]
	v_mfma_f32_16x16x32_bf16 v[60:63], v[152:155], v[160:163], v[60:63]
	v_mfma_f32_16x16x32_bf16 v[112:115], v[144:147], v[168:171], v[112:115]
	v_mfma_f32_16x16x32_bf16 v[44:47], v[152:155], v[168:171], v[44:47]
	v_mfma_f32_16x16x32_bf16 v[100:103], v[144:147], v[186:189], v[100:103]
	v_mfma_f32_16x16x32_bf16 v[48:51], v[152:155], v[186:189], v[48:51]
	v_mfma_f32_16x16x32_bf16 v[96:99], v[144:147], v[212:215], v[96:99]
	v_mfma_f32_16x16x32_bf16 v[36:39], v[152:155], v[212:215], v[36:39]
	v_mfma_f32_16x16x32_bf16 v[124:127], v[148:151], v[164:167], v[124:127]
	v_mfma_f32_16x16x32_bf16 v[60:63], v[156:159], v[164:167], v[60:63]
	v_mfma_f32_16x16x32_bf16 v[112:115], v[148:151], v[172:175], v[112:115]
	v_mfma_f32_16x16x32_bf16 v[44:47], v[156:159], v[172:175], v[44:47]
	v_mfma_f32_16x16x32_bf16 v[100:103], v[148:151], v[208:211], v[100:103]
	v_mfma_f32_16x16x32_bf16 v[48:51], v[156:159], v[208:211], v[48:51]
	v_mfma_f32_16x16x32_bf16 v[96:99], v[148:151], v[216:219], v[96:99]
	v_mfma_f32_16x16x32_bf16 v[36:39], v[156:159], v[216:219], v[36:39]
	s_setprio 0
	s_barrier
; #define PG8_LDA(dst, b, h) do { _Pragma("unroll") for (int m = 0; m < 4; ++m) _Pragma("unroll") for (int k = 0; k < 2; ++k) dst[m][k] = *(const LAS bf16x8*)(lds + PG8_SA(b, h) + aoff + m * 2048 + k * 1024); } while (0)
; #define PG8_MMA(ai, bj, At, Bt) do { __builtin_amdgcn_s_setprio(1); _Pragma("unroll") for (int m = 0; m < 4; ++m) _Pragma("unroll") for (int n = 0; n < 2; ++n) _Pragma("unroll") for (int k = 0; k < 2; ++k) \
;         acc[ai][bj][m][n] = __builtin_amdgcn_mfma_f32_16x16x32_bf16(Bt[n][k], At[m][k], acc[ai][bj][m][n], 0, 0, 0); __builtin_amdgcn_s_setprio(0); } while (0)
; #define PG8_WAIT_V(n) asm volatile("s_waitcnt vmcnt(" #n ")" ::: "memory")
; #define PG8_WAIT_L(n) asm volatile("s_waitcnt lgkmcnt(" #n ")" ::: "memory")
; #define PG8_BAR __builtin_amdgcn_s_barrier()
; #define PG8_SCHED __builtin_amdgcn_sched_barrier(0)
; template <class Epi, class Addr, bool ALIGN_EPI = true, class Order = StaticOrder>
; __device__ __forceinline__ void gemm_phase(LAS unsigned char* lds, const Gemm g, const Order& S, const Epi& E, const int wid) {
;     ...
;             PG8_LDA(At, 1, 1); PG8_STAGE(PG8_SB(1, 0), b3, voffB); PG8_STAGE(PG8_SB(1, 1), b3 + hstepB, voffB); PG8_STAGE(PG8_SA(1, 0), a3, voffA);
;             PG8_WAIT_V(8); PG8_WAIT_L(0); PG8_BAR; PG8_MMA(1, 0, At, B0); PG8_MMA(1, 1, At, B1); PG8_BAR; PG8_SCHED;
;         }
;         if constexpr (ALIGN_EPI) { if (wr == 0) PG8_BAR; }
;         E(acc, cur, wr, wc, fr, fq);
;         if (!has_next) break;
	ds_read_b128 v[160:163], v202 offset:49152
	ds_read_b128 v[164:167], v202 offset:50176
	ds_read_b128 v[168:171], v202 offset:51200
	ds_read_b128 v[172:175], v202 offset:52224
	ds_read_b128 v[186:189], v202 offset:53248
	ds_read_b128 v[208:211], v202 offset:54272
	ds_read_b128 v[212:215], v202 offset:55296
	ds_read_b128 v[216:219], v202 offset:56320
	s_add_u32 s12, s74, 0x80
	s_addc_u32 s13, s75, 0
	s_mov_b32 s19, m0
	s_mov_b32 m0, s89
	s_nop 0
	global_load_lds_dwordx4 v191, s[12:13]
	s_mov_b32 m0, s90
	s_nop 0
	global_load_lds_dwordx4 v193, s[12:13]
	s_mov_b32 m0, s19
	s_add_u32 s12, s74, 0x100080
	s_addc_u32 s13, s75, 0
	s_mov_b32 s19, m0
	s_mov_b32 m0, s94
	s_nop 0
	global_load_lds_dwordx4 v191, s[12:13]
	s_mov_b32 m0, s95
	s_nop 0
	global_load_lds_dwordx4 v193, s[12:13]
	s_mov_b32 m0, s19
	s_mov_b32 s12, m0
	s_mov_b32 m0, s91
	s_nop 0
	global_load_lds_dwordx4 v190, s[16:17]
	s_mov_b32 m0, s93
	s_nop 0
	global_load_lds_dwordx4 v192, s[16:17]
	s_mov_b32 m0, s12
	s_nop 15
	s_nop 15
	s_waitcnt vmcnt(8)
	s_waitcnt lgkmcnt(0)
	s_barrier
	s_setprio 1
	s_waitcnt lgkmcnt(7)
	v_mfma_f32_16x16x32_bf16 v[92:95], v[120:123], v[160:163], v[92:95]
	v_mfma_f32_16x16x32_bf16 v[24:27], v[136:139], v[160:163], v[24:27]
	s_waitcnt lgkmcnt(5)
	v_mfma_f32_16x16x32_bf16 v[84:87], v[120:123], v[168:171], v[84:87]
	v_mfma_f32_16x16x32_bf16 v[20:23], v[136:139], v[168:171], v[20:23]
	s_waitcnt lgkmcnt(3)
	v_mfma_f32_16x16x32_bf16 v[76:79], v[120:123], v[186:189], v[76:79]
	v_mfma_f32_16x16x32_bf16 v[0:3], v[136:139], v[186:189], v[0:3]
	s_waitcnt lgkmcnt(1)
	v_mfma_f32_16x16x32_bf16 v[72:75], v[120:123], v[212:215], v[72:75]
	v_mfma_f32_16x16x32_bf16 v[8:11], v[136:139], v[212:215], v[8:11]
	v_mfma_f32_16x16x32_bf16 v[92:95], v[132:135], v[164:167], v[92:95]
	v_mfma_f32_16x16x32_bf16 v[24:27], v[140:143], v[164:167], v[24:27]
	v_mfma_f32_16x16x32_bf16 v[84:87], v[132:135], v[172:175], v[84:87]
	v_mfma_f32_16x16x32_bf16 v[20:23], v[140:143], v[172:175], v[20:23]
	v_mfma_f32_16x16x32_bf16 v[76:79], v[132:135], v[208:211], v[76:79]
	v_mfma_f32_16x16x32_bf16 v[0:3], v[140:143], v[208:211], v[0:3]
	s_waitcnt lgkmcnt(0)
	v_mfma_f32_16x16x32_bf16 v[72:75], v[132:135], v[216:219], v[72:75]
	v_mfma_f32_16x16x32_bf16 v[8:11], v[140:143], v[216:219], v[8:11]
	s_setprio 0
	s_setprio 1
	v_mfma_f32_16x16x32_bf16 v[88:91], v[144:147], v[160:163], v[88:91]
	v_mfma_f32_16x16x32_bf16 v[28:31], v[152:155], v[160:163], v[28:31]
	v_mfma_f32_16x16x32_bf16 v[80:83], v[144:147], v[168:171], v[80:83]
	v_mfma_f32_16x16x32_bf16 v[16:19], v[152:155], v[168:171], v[16:19]
	v_mfma_f32_16x16x32_bf16 v[68:71], v[144:147], v[186:189], v[68:71]
	v_mfma_f32_16x16x32_bf16 v[4:7], v[152:155], v[186:189], v[4:7]
	v_mfma_f32_16x16x32_bf16 v[64:67], v[144:147], v[212:215], v[64:67]
	v_mfma_f32_16x16x32_bf16 v[12:15], v[152:155], v[212:215], v[12:15]
	v_mfma_f32_16x16x32_bf16 v[88:91], v[148:151], v[164:167], v[88:91]
	v_mfma_f32_16x16x32_bf16 v[28:31], v[156:159], v[164:167], v[28:31]
	v_mfma_f32_16x16x32_bf16 v[80:83], v[148:151], v[172:175], v[80:83]
	v_mfma_f32_16x16x32_bf16 v[16:19], v[156:159], v[172:175], v[16:19]
	v_mfma_f32_16x16x32_bf16 v[68:71], v[148:151], v[208:211], v[68:71]
	v_mfma_f32_16x16x32_bf16 v[4:7], v[156:159], v[208:211], v[4:7]
	v_mfma_f32_16x16x32_bf16 v[64:67], v[148:151], v[216:219], v[64:67]
	v_mfma_f32_16x16x32_bf16 v[12:15], v[156:159], v[216:219], v[12:15]
	s_setprio 0
	s_barrier
	s_add_i32 s18, s18, 2
	s_add_u32 vcc_lo, vcc_lo, 0x100
	s_addc_u32 vcc_hi, vcc_hi, 0
	s_cmp_gt_u32 s18, 61
	s_mov_b64 s[12:13], s[14:15]
	s_cbranch_scc0 .LBB0_951
	s_and_b64 vcc, exec, s[4:5]
	s_cbranch_vccz .LBB0_995
	s_barrier
	v_cmp_gt_i32_e32 vcc, 15, v194
	s_mov_b64 s[14:15], -1
	s_and_saveexec_b64 s[12:13], vcc
	s_cbranch_execnz .LBB0_996
